# as v33 but barrier 8 MFMAs early in the three generic GEMM loops
# baseline (speedup 1.0000x reference)
; #define PG8_STAGE(bufoff, gbase, voff) do { _Pragma("unroll") for (int _i = 0; _i < 2; ++_i) \
;         __builtin_amdgcn_global_load_lds((const unsigned*)((const char*)(gbase) + (voff)[_i]), (LAS unsigned*)(lds + (bufoff) + ldsw + _i * 8192), 16, 0, 0); } while (0)
; #define PG8_LDA(dst, b, h) do { _Pragma("unroll") for (int m = 0; m < 4; ++m) _Pragma("unroll") for (int k = 0; k < 2; ++k) dst[m][k] = *(const LAS bf16x8*)(lds + PG8_SA(b, h) + aoff + m * 2048 + k * 1024); } while (0)
; #define PG8_WAIT_V(n) asm volatile("s_waitcnt vmcnt(" #n ")" ::: "memory")
; #define PG8_WAIT_L(n) asm volatile("s_waitcnt lgkmcnt(" #n ")" ::: "memory")
; template <class Epi, class Sched>
; __device__ __forceinline__ void gemm_phase(LAS unsigned char* lds, const Gemm g, Sched S, const Epi& E) {
;     ...
;         const bool has_next = S.next(ui + 1, nxt);
;         const char* nA = has_next ? (const char*)g.A + a_off(g, nxt) : cA; const char* nB = has_next ? (const char*)g.Bt + b_off(g, nxt) : cB;
;         for (int t = 0; t < nt; t += 2) {
;             const bool last = (t == nt - 2);
;             const char* a1 = cA + (size_t)(t + 1) * kstep;
;             const char* a2 = last ? nA : cA + (size_t)(t + 2) * kstep; const char* b2 = last ? nB : cB + (size_t)(t + 2) * kstep;
;             const char* a3 = a2 + kstep; const char* b3 = b2 + kstep;
;             PG8_LDB(B0, 0, 0); PG8_LDB(B1, 0, 1); PG8_SCHED; PG8_LDA(At, 0, 0); PG8_STAGE(PG8_SA(1, 1), a1 + hstepA, voffA);
;             PG8_WAIT_V(8); PG8_WAIT_L(0); PG8_BAR; PG8_MMA(0, 0, At, B0); PG8_MMA(0, 1, At, B1); PG8_BAR; PG8_SCHED;
;             PG8_LDA(At, 0, 1); PG8_STAGE(PG8_SB(0, 0), b2, voffB); PG8_STAGE(PG8_SB(0, 1), b2 + hstepB, voffB); PG8_STAGE(PG8_SA(0, 0), a2, voffA);
;             PG8_WAIT_V(8); PG8_WAIT_L(0); PG8_BAR; PG8_MMA(1, 0, At, B0); PG8_MMA(1, 1, At, B1); PG8_BAR; PG8_SCHED;
;             PG8_LDB(B0, 1, 0); PG8_LDB(B1, 1, 1); PG8_SCHED; PG8_LDA(At, 1, 0); PG8_STAGE(PG8_SA(0, 1), a2 + hstepA, voffA);
;             PG8_WAIT_V(8); PG8_WAIT_L(0); PG8_BAR; PG8_MMA(0, 0, At, B0); PG8_MMA(0, 1, At, B1); PG8_BAR; PG8_SCHED;
;             PG8_LDA(At, 1, 1); PG8_STAGE(PG8_SB(1, 0), b3, voffB); PG8_STAGE(PG8_SB(1, 1), b3 + hstepB, voffB); PG8_STAGE(PG8_SA(1, 0), a3, voffA);
;             PG8_WAIT_V(8); PG8_WAIT_L(0); PG8_BAR; PG8_MMA(1, 0, At, B0); PG8_MMA(1, 1, At, B1); PG8_BAR; PG8_SCHED;
.LBB0_630:
	s_add_i32 s67, s65, 2
	s_add_u32 s2, s0, 0xfffc0080
	s_addc_u32 s3, s1, -1
	s_add_i32 s99, 0, 0x10000
	s_cmp_eq_u32 s70, s65
	s_cselect_b32 vcc_hi, s55, s3
	s_cselect_b32 vcc_lo, s54, s2
	s_cselect_b32 s77, s45, s64
	s_cselect_b32 s76, s44, s63
	s_add_i32 s65, 0, 0x14000
	v_add_u32_e32 v142, s99, v180
	v_add_u32_e32 v158, s65, v180
	ds_read_b128 v[130:133], v142
	ds_read_b128 v[134:137], v142 offset:1024
	ds_read_b128 v[138:141], v142 offset:2048
	ds_read_b128 v[142:145], v142 offset:3072
	ds_read_b128 v[146:149], v158
	ds_read_b128 v[150:153], v158 offset:1024
	ds_read_b128 v[154:157], v158 offset:2048
	ds_read_b128 v[158:161], v158 offset:3072
	s_add_i32 m0, s53, 0xc000
	ds_read_b128 v[174:177], v191
	ds_read_b128 v[192:195], v191 offset:1024
	ds_read_b128 v[196:199], v191 offset:2048
	ds_read_b128 v[200:203], v191 offset:3072
	ds_read_b128 v[204:207], v191 offset:4096
	ds_read_b128 v[208:211], v191 offset:5120
	ds_read_b128 v[212:215], v191 offset:6144
	ds_read_b128 v[216:219], v191 offset:7168
	global_load_lds_dwordx4 v172, s[0:1]
	s_add_i32 m0, s53, 0xe000
	s_nop 0
	global_load_lds_dwordx4 v170, s[0:1]
	s_waitcnt vmcnt(8)
	s_waitcnt lgkmcnt(0)
	s_barrier
	s_setprio 1
	s_waitcnt lgkmcnt(0)
	v_mfma_f32_16x16x32_bf16 v[126:129], v[130:133], v[174:177], v[126:129]
	v_mfma_f32_16x16x32_bf16 v[122:125], v[138:141], v[174:177], v[122:125]
	v_mfma_f32_16x16x32_bf16 v[114:117], v[130:133], v[196:199], v[114:117]
	v_mfma_f32_16x16x32_bf16 v[106:109], v[138:141], v[196:199], v[106:109]
	v_mfma_f32_16x16x32_bf16 v[98:101], v[130:133], v[204:207], v[98:101]
	v_mfma_f32_16x16x32_bf16 v[90:93], v[138:141], v[204:207], v[90:93]
	v_mfma_f32_16x16x32_bf16 v[82:85], v[130:133], v[212:215], v[82:85]
	v_mfma_f32_16x16x32_bf16 v[74:77], v[138:141], v[212:215], v[74:77]
	v_mfma_f32_16x16x32_bf16 v[126:129], v[134:137], v[192:195], v[126:129]
	v_mfma_f32_16x16x32_bf16 v[122:125], v[142:145], v[192:195], v[122:125]
	v_mfma_f32_16x16x32_bf16 v[114:117], v[134:137], v[200:203], v[114:117]
	v_mfma_f32_16x16x32_bf16 v[106:109], v[142:145], v[200:203], v[106:109]
	v_mfma_f32_16x16x32_bf16 v[98:101], v[134:137], v[208:211], v[98:101]
	v_mfma_f32_16x16x32_bf16 v[90:93], v[142:145], v[208:211], v[90:93]
	v_mfma_f32_16x16x32_bf16 v[82:85], v[134:137], v[216:219], v[82:85]
	v_mfma_f32_16x16x32_bf16 v[74:77], v[142:145], v[216:219], v[74:77]
	s_setprio 0
	s_setprio 1
	v_mfma_f32_16x16x32_bf16 v[118:121], v[146:149], v[174:177], v[118:121]
	v_mfma_f32_16x16x32_bf16 v[110:113], v[154:157], v[174:177], v[110:113]
	v_mfma_f32_16x16x32_bf16 v[102:105], v[146:149], v[196:199], v[102:105]
	v_mfma_f32_16x16x32_bf16 v[94:97], v[154:157], v[196:199], v[94:97]
	v_mfma_f32_16x16x32_bf16 v[86:89], v[146:149], v[204:207], v[86:89]
	v_mfma_f32_16x16x32_bf16 v[78:81], v[154:157], v[204:207], v[78:81]
	v_mfma_f32_16x16x32_bf16 v[70:73], v[146:149], v[212:215], v[70:73]
	v_mfma_f32_16x16x32_bf16 v[66:69], v[154:157], v[212:215], v[66:69]
	s_setprio 2
	s_barrier
	v_mfma_f32_16x16x32_bf16 v[118:121], v[150:153], v[192:195], v[118:121]
	v_mfma_f32_16x16x32_bf16 v[110:113], v[158:161], v[192:195], v[110:113]
	v_mfma_f32_16x16x32_bf16 v[102:105], v[150:153], v[200:203], v[102:105]
	v_mfma_f32_16x16x32_bf16 v[94:97], v[158:161], v[200:203], v[94:97]
	v_mfma_f32_16x16x32_bf16 v[86:89], v[150:153], v[208:211], v[86:89]
	v_mfma_f32_16x16x32_bf16 v[78:81], v[158:161], v[208:211], v[78:81]
	v_mfma_f32_16x16x32_bf16 v[70:73], v[150:153], v[216:219], v[70:73]
	v_mfma_f32_16x16x32_bf16 v[66:69], v[158:161], v[216:219], v[66:69]
	s_setprio 0
	s_add_i32 s2, s99, s43
	s_mov_b32 m0, s2
	ds_read_b128 v[174:177], v191 offset:16384
	ds_read_b128 v[192:195], v191 offset:17408
	ds_read_b128 v[196:199], v191 offset:18432
	ds_read_b128 v[200:203], v191 offset:19456
	ds_read_b128 v[204:207], v191 offset:20480
	ds_read_b128 v[208:211], v191 offset:21504
	ds_read_b128 v[212:215], v191 offset:22528
	ds_read_b128 v[216:219], v191 offset:23552
	global_load_lds_dwordx4 v0, s[76:77]
	s_add_i32 m0, s2, 0x2000
	s_add_u32 s2, s76, 0x40000
	s_addc_u32 s3, s77, 0
	s_add_i32 s65, s65, s43
	global_load_lds_dwordx4 v168, s[76:77]
	s_mov_b32 m0, s65
	s_nop 0
	global_load_lds_dwordx4 v0, s[2:3]
	s_add_i32 m0, s65, 0x2000
	s_nop 0
	global_load_lds_dwordx4 v168, s[2:3]
	s_mov_b32 m0, s53
	s_nop 0
	global_load_lds_dwordx4 v164, vcc
	s_mov_b32 m0, s85
	s_nop 0
	global_load_lds_dwordx4 v166, vcc
	s_waitcnt vmcnt(8)
	s_waitcnt lgkmcnt(0)
	s_barrier
	s_setprio 1
	s_waitcnt lgkmcnt(0)
	v_mfma_f32_16x16x32_bf16 v[62:65], v[130:133], v[174:177], v[62:65]
	v_mfma_f32_16x16x32_bf16 v[58:61], v[138:141], v[174:177], v[58:61]
	v_mfma_f32_16x16x32_bf16 v[50:53], v[130:133], v[196:199], v[50:53]
	v_mfma_f32_16x16x32_bf16 v[42:45], v[138:141], v[196:199], v[42:45]
	v_mfma_f32_16x16x32_bf16 v[34:37], v[130:133], v[204:207], v[34:37]
	v_mfma_f32_16x16x32_bf16 v[26:29], v[138:141], v[204:207], v[26:29]
	v_mfma_f32_16x16x32_bf16 v[18:21], v[130:133], v[212:215], v[18:21]
	v_mfma_f32_16x16x32_bf16 v[10:13], v[138:141], v[212:215], v[10:13]
	v_mfma_f32_16x16x32_bf16 v[62:65], v[134:137], v[192:195], v[62:65]
	v_mfma_f32_16x16x32_bf16 v[58:61], v[142:145], v[192:195], v[58:61]
	v_mfma_f32_16x16x32_bf16 v[50:53], v[134:137], v[200:203], v[50:53]
	v_mfma_f32_16x16x32_bf16 v[42:45], v[142:145], v[200:203], v[42:45]
	v_mfma_f32_16x16x32_bf16 v[34:37], v[134:137], v[208:211], v[34:37]
	v_mfma_f32_16x16x32_bf16 v[26:29], v[142:145], v[208:211], v[26:29]
	v_mfma_f32_16x16x32_bf16 v[18:21], v[134:137], v[216:219], v[18:21]
	v_mfma_f32_16x16x32_bf16 v[10:13], v[142:145], v[216:219], v[10:13]
	s_setprio 0
	s_setprio 1
	v_mfma_f32_16x16x32_bf16 v[54:57], v[146:149], v[174:177], v[54:57]
	v_mfma_f32_16x16x32_bf16 v[46:49], v[154:157], v[174:177], v[46:49]
	v_mfma_f32_16x16x32_bf16 v[38:41], v[146:149], v[196:199], v[38:41]
	v_mfma_f32_16x16x32_bf16 v[30:33], v[154:157], v[196:199], v[30:33]
	v_mfma_f32_16x16x32_bf16 v[22:25], v[146:149], v[204:207], v[22:25]
	v_mfma_f32_16x16x32_bf16 v[14:17], v[154:157], v[204:207], v[14:17]
	v_mfma_f32_16x16x32_bf16 v[6:9], v[146:149], v[212:215], v[6:9]
	v_mfma_f32_16x16x32_bf16 v[2:5], v[154:157], v[212:215], v[2:5]
	s_setprio 2
	s_barrier
; #define PG8_STAGE(bufoff, gbase, voff) do { _Pragma("unroll") for (int _i = 0; _i < 2; ++_i) \
;         __builtin_amdgcn_global_load_lds((const unsigned*)((const char*)(gbase) + (voff)[_i]), (LAS unsigned*)(lds + (bufoff) + ldsw + _i * 8192), 16, 0, 0); } while (0)
; #define PG8_LDA(dst, b, h) do { _Pragma("unroll") for (int m = 0; m < 4; ++m) _Pragma("unroll") for (int k = 0; k < 2; ++k) dst[m][k] = *(const LAS bf16x8*)(lds + PG8_SA(b, h) + aoff + m * 2048 + k * 1024); } while (0)
; #define PG8_MMA(ai, bj, At, Bt) do { __builtin_amdgcn_s_setprio(1); _Pragma("unroll") for (int m = 0; m < 4; ++m) _Pragma("unroll") for (int n = 0; n < 2; ++n) _Pragma("unroll") for (int k = 0; k < 2; ++k) \
;         acc[ai][bj][m][n] = __builtin_amdgcn_mfma_f32_16x16x32_bf16(Bt[n][k], At[m][k], acc[ai][bj][m][n], 0, 0, 0); __builtin_amdgcn_s_setprio(0); } while (0)
; #define PG8_WAIT_V(n) asm volatile("s_waitcnt vmcnt(" #n ")" ::: "memory")
; #define PG8_WAIT_L(n) asm volatile("s_waitcnt lgkmcnt(" #n ")" ::: "memory")
; #define PG8_BAR __builtin_amdgcn_s_barrier()
; #define PG8_SCHED __builtin_amdgcn_sched_barrier(0)
; template <class Epi, class Sched>
; __device__ __forceinline__ void gemm_phase(LAS unsigned char* lds, const Gemm g, Sched S, const Epi& E) {
;     ...
;             PG8_WAIT_V(8); PG8_WAIT_L(0); PG8_BAR; PG8_MMA(0, 0, At, B0); PG8_MMA(0, 1, At, B1); PG8_BAR; PG8_SCHED;
;             PG8_LDA(At, 1, 1); PG8_STAGE(PG8_SB(1, 0), b3, voffB); PG8_STAGE(PG8_SB(1, 1), b3 + hstepB, voffB); PG8_STAGE(PG8_SA(1, 0), a3, voffA);
	v_mfma_f32_16x16x32_bf16 v[54:57], v[150:153], v[192:195], v[54:57]
	v_mfma_f32_16x16x32_bf16 v[46:49], v[158:161], v[192:195], v[46:49]
	v_mfma_f32_16x16x32_bf16 v[38:41], v[150:153], v[200:203], v[38:41]
	v_mfma_f32_16x16x32_bf16 v[30:33], v[158:161], v[200:203], v[30:33]
	v_mfma_f32_16x16x32_bf16 v[22:25], v[150:153], v[208:211], v[22:25]
	v_mfma_f32_16x16x32_bf16 v[14:17], v[158:161], v[208:211], v[14:17]
	v_mfma_f32_16x16x32_bf16 v[6:9], v[150:153], v[216:219], v[6:9]
	v_mfma_f32_16x16x32_bf16 v[2:5], v[158:161], v[216:219], v[2:5]
	s_setprio 0
	s_add_i32 s65, 0, 0x18000
	s_add_i32 s99, 0, 0x1c000
	v_add_u32_e32 v142, s65, v180
	v_add_u32_e32 v158, s99, v180
	ds_read_b128 v[130:133], v142
	ds_read_b128 v[134:137], v142 offset:1024
	ds_read_b128 v[138:141], v142 offset:2048
	ds_read_b128 v[142:145], v142 offset:3072
	ds_read_b128 v[146:149], v158
	ds_read_b128 v[150:153], v158 offset:1024
	ds_read_b128 v[154:157], v158 offset:2048
	ds_read_b128 v[158:161], v158 offset:3072
	s_add_u32 s2, vcc_lo, 0x40000
	s_addc_u32 s3, vcc_hi, 0
	s_mov_b32 m0, s18
	ds_read_b128 v[174:177], v191 offset:32768
	ds_read_b128 v[192:195], v191 offset:33792
	ds_read_b128 v[196:199], v191 offset:34816
	ds_read_b128 v[200:203], v191 offset:35840
	ds_read_b128 v[204:207], v191 offset:36864
	ds_read_b128 v[208:211], v191 offset:37888
	ds_read_b128 v[212:215], v191 offset:38912
	ds_read_b128 v[216:219], v191 offset:39936
	global_load_lds_dwordx4 v164, s[2:3]
	s_mov_b32 m0, s19
	s_nop 0
	global_load_lds_dwordx4 v166, s[2:3]
	s_waitcnt vmcnt(8)
	s_waitcnt lgkmcnt(0)
	s_barrier
	s_setprio 1
	s_waitcnt lgkmcnt(0)
	v_mfma_f32_16x16x32_bf16 v[126:129], v[130:133], v[174:177], v[126:129]
	v_mfma_f32_16x16x32_bf16 v[122:125], v[138:141], v[174:177], v[122:125]
	v_mfma_f32_16x16x32_bf16 v[114:117], v[130:133], v[196:199], v[114:117]
	v_mfma_f32_16x16x32_bf16 v[106:109], v[138:141], v[196:199], v[106:109]
	v_mfma_f32_16x16x32_bf16 v[98:101], v[130:133], v[204:207], v[98:101]
	v_mfma_f32_16x16x32_bf16 v[90:93], v[138:141], v[204:207], v[90:93]
	v_mfma_f32_16x16x32_bf16 v[82:85], v[130:133], v[212:215], v[82:85]
	v_mfma_f32_16x16x32_bf16 v[74:77], v[138:141], v[212:215], v[74:77]
	v_mfma_f32_16x16x32_bf16 v[126:129], v[134:137], v[192:195], v[126:129]
	v_mfma_f32_16x16x32_bf16 v[122:125], v[142:145], v[192:195], v[122:125]
	v_mfma_f32_16x16x32_bf16 v[114:117], v[134:137], v[200:203], v[114:117]
	v_mfma_f32_16x16x32_bf16 v[106:109], v[142:145], v[200:203], v[106:109]
	v_mfma_f32_16x16x32_bf16 v[98:101], v[134:137], v[208:211], v[98:101]
	v_mfma_f32_16x16x32_bf16 v[90:93], v[142:145], v[208:211], v[90:93]
	v_mfma_f32_16x16x32_bf16 v[82:85], v[134:137], v[216:219], v[82:85]
	v_mfma_f32_16x16x32_bf16 v[74:77], v[142:145], v[216:219], v[74:77]
	s_setprio 0
	s_setprio 1
	v_mfma_f32_16x16x32_bf16 v[118:121], v[146:149], v[174:177], v[118:121]
	v_mfma_f32_16x16x32_bf16 v[110:113], v[154:157], v[174:177], v[110:113]
	v_mfma_f32_16x16x32_bf16 v[102:105], v[146:149], v[196:199], v[102:105]
	v_mfma_f32_16x16x32_bf16 v[94:97], v[154:157], v[196:199], v[94:97]
	v_mfma_f32_16x16x32_bf16 v[86:89], v[146:149], v[204:207], v[86:89]
	v_mfma_f32_16x16x32_bf16 v[78:81], v[154:157], v[204:207], v[78:81]
	v_mfma_f32_16x16x32_bf16 v[70:73], v[146:149], v[212:215], v[70:73]
	v_mfma_f32_16x16x32_bf16 v[66:69], v[154:157], v[212:215], v[66:69]
	s_setprio 2
	s_barrier
; #define PG8_STAGE(bufoff, gbase, voff) do { _Pragma("unroll") for (int _i = 0; _i < 2; ++_i) \
;         __builtin_amdgcn_global_load_lds((const unsigned*)((const char*)(gbase) + (voff)[_i]), (LAS unsigned*)(lds + (bufoff) + ldsw + _i * 8192), 16, 0, 0); } while (0)
; #define PG8_LDA(dst, b, h) do { _Pragma("unroll") for (int m = 0; m < 4; ++m) _Pragma("unroll") for (int k = 0; k < 2; ++k) dst[m][k] = *(const LAS bf16x8*)(lds + PG8_SA(b, h) + aoff + m * 2048 + k * 1024); } while (0)
; #define PG8_MMA(ai, bj, At, Bt) do { __builtin_amdgcn_s_setprio(1); _Pragma("unroll") for (int m = 0; m < 4; ++m) _Pragma("unroll") for (int n = 0; n < 2; ++n) _Pragma("unroll") for (int k = 0; k < 2; ++k) \
;         acc[ai][bj][m][n] = __builtin_amdgcn_mfma_f32_16x16x32_bf16(Bt[n][k], At[m][k], acc[ai][bj][m][n], 0, 0, 0); __builtin_amdgcn_s_setprio(0); } while (0)
; #define PG8_WAIT_V(n) asm volatile("s_waitcnt vmcnt(" #n ")" ::: "memory")
; #define PG8_WAIT_L(n) asm volatile("s_waitcnt lgkmcnt(" #n ")" ::: "memory")
; #define PG8_BAR __builtin_amdgcn_s_barrier()
; #define PG8_SCHED __builtin_amdgcn_sched_barrier(0)
; template <class Epi, class Sched>
; __device__ __forceinline__ void gemm_phase(LAS unsigned char* lds, const Gemm g, Sched S, const Epi& E) {
;     ...
;             PG8_LDA(At, 1, 1); PG8_STAGE(PG8_SB(1, 0), b3, voffB); PG8_STAGE(PG8_SB(1, 1), b3 + hstepB, voffB); PG8_STAGE(PG8_SA(1, 0), a3, voffA);
;             PG8_WAIT_V(8); PG8_WAIT_L(0); PG8_BAR; PG8_MMA(1, 0, At, B0); PG8_MMA(1, 1, At, B1); PG8_BAR; PG8_SCHED;
;     ...
;         if (wr == 0) PG8_BAR;
	v_mfma_f32_16x16x32_bf16 v[118:121], v[150:153], v[192:195], v[118:121]
	v_mfma_f32_16x16x32_bf16 v[110:113], v[158:161], v[192:195], v[110:113]
	v_mfma_f32_16x16x32_bf16 v[102:105], v[150:153], v[200:203], v[102:105]
	v_mfma_f32_16x16x32_bf16 v[94:97], v[158:161], v[200:203], v[94:97]
	v_mfma_f32_16x16x32_bf16 v[86:89], v[150:153], v[208:211], v[86:89]
	v_mfma_f32_16x16x32_bf16 v[78:81], v[158:161], v[208:211], v[78:81]
	v_mfma_f32_16x16x32_bf16 v[70:73], v[150:153], v[216:219], v[70:73]
	v_mfma_f32_16x16x32_bf16 v[66:69], v[158:161], v[216:219], v[66:69]
	s_setprio 0
	s_add_i32 s2, s65, s43
	s_add_u32 s100, s76, 0x80
	s_addc_u32 s101, s77, 0
	s_mov_b32 m0, s2
	ds_read_b128 v[174:177], v191 offset:49152
	ds_read_b128 v[192:195], v191 offset:50176
	ds_read_b128 v[196:199], v191 offset:51200
	ds_read_b128 v[200:203], v191 offset:52224
	ds_read_b128 v[204:207], v191 offset:53248
	ds_read_b128 v[208:211], v191 offset:54272
	ds_read_b128 v[212:215], v191 offset:55296
	ds_read_b128 v[216:219], v191 offset:56320
	global_load_lds_dwordx4 v0, s[100:101]
	s_add_i32 m0, s2, 0x2000
	s_add_u32 s2, s76, 0x40080
	s_addc_u32 s3, s77, 0
	s_add_i32 s65, s99, s43
	global_load_lds_dwordx4 v168, s[100:101]
	s_mov_b32 m0, s65
	s_nop 0
	global_load_lds_dwordx4 v0, s[2:3]
	s_add_i32 m0, s65, 0x2000
	s_nop 0
	global_load_lds_dwordx4 v168, s[2:3]
	s_add_u32 s100, vcc_lo, 0x80
	s_addc_u32 s101, vcc_hi, 0
	s_mov_b32 m0, s71
	s_nop 0
	global_load_lds_dwordx4 v164, s[100:101]
	s_mov_b32 m0, s40
	s_nop 0
	global_load_lds_dwordx4 v166, s[100:101]
	s_waitcnt vmcnt(8)
	s_waitcnt lgkmcnt(0)
	s_barrier
	s_setprio 1
	s_waitcnt lgkmcnt(0)
	v_mfma_f32_16x16x32_bf16 v[62:65], v[130:133], v[174:177], v[62:65]
	v_mfma_f32_16x16x32_bf16 v[58:61], v[138:141], v[174:177], v[58:61]
	v_mfma_f32_16x16x32_bf16 v[50:53], v[130:133], v[196:199], v[50:53]
	v_mfma_f32_16x16x32_bf16 v[42:45], v[138:141], v[196:199], v[42:45]
	v_mfma_f32_16x16x32_bf16 v[34:37], v[130:133], v[204:207], v[34:37]
	v_mfma_f32_16x16x32_bf16 v[26:29], v[138:141], v[204:207], v[26:29]
	v_mfma_f32_16x16x32_bf16 v[18:21], v[130:133], v[212:215], v[18:21]
	v_mfma_f32_16x16x32_bf16 v[10:13], v[138:141], v[212:215], v[10:13]
	v_mfma_f32_16x16x32_bf16 v[62:65], v[134:137], v[192:195], v[62:65]
	v_mfma_f32_16x16x32_bf16 v[58:61], v[142:145], v[192:195], v[58:61]
	v_mfma_f32_16x16x32_bf16 v[50:53], v[134:137], v[200:203], v[50:53]
	v_mfma_f32_16x16x32_bf16 v[42:45], v[142:145], v[200:203], v[42:45]
	v_mfma_f32_16x16x32_bf16 v[34:37], v[134:137], v[208:211], v[34:37]
	v_mfma_f32_16x16x32_bf16 v[26:29], v[142:145], v[208:211], v[26:29]
	v_mfma_f32_16x16x32_bf16 v[18:21], v[134:137], v[216:219], v[18:21]
	v_mfma_f32_16x16x32_bf16 v[10:13], v[142:145], v[216:219], v[10:13]
	s_setprio 0
	s_setprio 1
	v_mfma_f32_16x16x32_bf16 v[54:57], v[146:149], v[174:177], v[54:57]
	v_mfma_f32_16x16x32_bf16 v[46:49], v[154:157], v[174:177], v[46:49]
	v_mfma_f32_16x16x32_bf16 v[38:41], v[146:149], v[196:199], v[38:41]
	v_mfma_f32_16x16x32_bf16 v[30:33], v[154:157], v[196:199], v[30:33]
	v_mfma_f32_16x16x32_bf16 v[22:25], v[146:149], v[204:207], v[22:25]
	v_mfma_f32_16x16x32_bf16 v[14:17], v[154:157], v[204:207], v[14:17]
	v_mfma_f32_16x16x32_bf16 v[6:9], v[146:149], v[212:215], v[6:9]
	v_mfma_f32_16x16x32_bf16 v[2:5], v[154:157], v[212:215], v[2:5]
	s_setprio 2
	s_barrier
	v_mfma_f32_16x16x32_bf16 v[54:57], v[150:153], v[192:195], v[54:57]
	v_mfma_f32_16x16x32_bf16 v[46:49], v[158:161], v[192:195], v[46:49]
	v_mfma_f32_16x16x32_bf16 v[38:41], v[150:153], v[200:203], v[38:41]
	v_mfma_f32_16x16x32_bf16 v[30:33], v[158:161], v[200:203], v[30:33]
	v_mfma_f32_16x16x32_bf16 v[22:25], v[150:153], v[208:211], v[22:25]
	v_mfma_f32_16x16x32_bf16 v[14:17], v[158:161], v[208:211], v[14:17]
	v_mfma_f32_16x16x32_bf16 v[6:9], v[150:153], v[216:219], v[6:9]
	v_mfma_f32_16x16x32_bf16 v[2:5], v[158:161], v[216:219], v[2:5]
	s_setprio 0
	s_add_u32 s63, s63, 0x100
	s_addc_u32 s64, s64, 0
	s_add_u32 s0, s0, 0x100
	s_addc_u32 s1, s1, 0
	s_cmp_ge_u32 s67, s58
	s_mov_b32 s65, s67
	s_cbranch_scc0 .LBB0_630
	s_and_b64 vcc, exec, s[94:95]
	s_cbranch_vccz .LBB0_635
	s_barrier
	s_and_b64 s[0:1], s[96:97], s[10:11]
	s_andn2_b64 vcc, exec, s[0:1]
	s_mov_b64 s[0:1], -1
	s_cbranch_vccnz .LBB0_636

; #define PG8_STAGE(bufoff, gbase, voff) do { _Pragma("unroll") for (int _i = 0; _i < 2; ++_i) \
;         __builtin_amdgcn_global_load_lds((const unsigned*)((const char*)(gbase) + (voff)[_i]), (LAS unsigned*)(lds + (bufoff) + ldsw + _i * 8192), 16, 0, 0); } while (0)
; #define PG8_LDA(dst, b, h) do { _Pragma("unroll") for (int m = 0; m < 4; ++m) _Pragma("unroll") for (int k = 0; k < 2; ++k) dst[m][k] = *(const LAS bf16x8*)(lds + PG8_SA(b, h) + aoff + m * 2048 + k * 1024); } while (0)
; #define PG8_LDB(dst, b, h) do { _Pragma("unroll") for (int n = 0; n < 2; ++n) _Pragma("unroll") for (int k = 0; k < 2; ++k) dst[n][k] = *(const LAS bf16x8*)(lds + PG8_SB(b, h) + boff + n * 2048 + k * 1024); } while (0)
; #define PG8_WAIT_V(n) asm volatile("s_waitcnt vmcnt(" #n ")" ::: "memory")
; #define PG8_WAIT_L(n) asm volatile("s_waitcnt lgkmcnt(" #n ")" ::: "memory")
; #define PG8_BAR __builtin_amdgcn_s_barrier()
; template <class Epi, class Sched>
; __device__ __forceinline__ void gemm_phase(LAS unsigned char* lds, const Gemm g, Sched S, const Epi& E) {
;     ...
;         const bool has_next = S.next(ui + 1, nxt);
;         const char* nA = has_next ? (const char*)g.A + a_off(g, nxt) : cA; const char* nB = has_next ? (const char*)g.Bt + b_off(g, nxt) : cB;
;         for (int t = 0; t < nt; t += 2) {
;             const bool last = (t == nt - 2);
;             const char* a1 = cA + (size_t)(t + 1) * kstep;
;             const char* a2 = last ? nA : cA + (size_t)(t + 2) * kstep; const char* b2 = last ? nB : cB + (size_t)(t + 2) * kstep;
;             const char* a3 = a2 + kstep; const char* b3 = b2 + kstep;
;             PG8_LDB(B0, 0, 0); PG8_LDB(B1, 0, 1); PG8_SCHED; PG8_LDA(At, 0, 0); PG8_STAGE(PG8_SA(1, 1), a1 + hstepA, voffA);
;             PG8_WAIT_V(8); PG8_WAIT_L(0); PG8_BAR; PG8_MMA(0, 0, At, B0); PG8_MMA(0, 1, At, B1); PG8_BAR; PG8_SCHED;
;             PG8_LDA(At, 0, 1); PG8_STAGE(PG8_SB(0, 0), b2, voffB); PG8_STAGE(PG8_SB(0, 1), b2 + hstepB, voffB); PG8_STAGE(PG8_SA(0, 0), a2, voffA);
;             PG8_WAIT_V(8); PG8_WAIT_L(0); PG8_BAR; PG8_MMA(1, 0, At, B0); PG8_MMA(1, 1, At, B1); PG8_BAR; PG8_SCHED;
;             PG8_LDB(B0, 1, 0); PG8_LDB(B1, 1, 1); PG8_SCHED; PG8_LDA(At, 1, 0); PG8_STAGE(PG8_SA(0, 1), a2 + hstepA, voffA);
;             PG8_WAIT_V(8); PG8_WAIT_L(0); PG8_BAR; PG8_MMA(0, 0, At, B0); PG8_MMA(0, 1, At, B1); PG8_BAR; PG8_SCHED;
.LBB0_727:
	s_add_i32 s21, s20, 2
	s_add_u32 s3, s42, 0x80
	s_addc_u32 s35, s43, 0
	s_add_i32 s52, 0, 0x10000
	s_cmp_eq_u32 s99, s20
	s_cselect_b32 s45, s89, s35
	s_cselect_b32 s44, s88, s3
	s_cselect_b32 s41, s91, s19
	s_cselect_b32 s40, s90, s11
	s_add_i32 s3, 0, 0x14000
	v_add_u32_e32 v126, s52, v192
	v_add_u32_e32 v170, s3, v192
	ds_read_b128 v[114:117], v126
	ds_read_b128 v[118:121], v126 offset:1024
	ds_read_b128 v[122:125], v126 offset:2048
	ds_read_b128 v[126:129], v126 offset:3072
	ds_read_b128 v[130:133], v170
	ds_read_b128 v[134:137], v170 offset:1024
	ds_read_b128 v[166:169], v170 offset:2048
	ds_read_b128 v[170:173], v170 offset:3072
	s_add_i32 m0, s85, 0xc000
	ds_read_b128 v[174:177], v194
	ds_read_b128 v[178:181], v194 offset:1024
	ds_read_b128 v[196:199], v194 offset:2048
	ds_read_b128 v[200:203], v194 offset:3072
	ds_read_b128 v[204:207], v194 offset:4096
	ds_read_b128 v[208:211], v194 offset:5120
	ds_read_b128 v[212:215], v194 offset:6144
	ds_read_b128 v[216:219], v194 offset:7168
	global_load_lds_dwordx4 v164, s[42:43]
	s_add_i32 m0, s85, 0xe000
	s_nop 0
	global_load_lds_dwordx4 v160, s[42:43]
	s_waitcnt vmcnt(8)
	s_waitcnt lgkmcnt(0)
	s_barrier
	s_setprio 1
	s_waitcnt lgkmcnt(0)
	v_mfma_f32_16x16x32_bf16 v[150:153], v[114:117], v[174:177], v[150:153]
	v_mfma_f32_16x16x32_bf16 v[146:149], v[122:125], v[174:177], v[146:149]
	v_mfma_f32_16x16x32_bf16 v[110:113], v[114:117], v[196:199], v[110:113]
	v_mfma_f32_16x16x32_bf16 v[106:109], v[122:125], v[196:199], v[106:109]
	v_mfma_f32_16x16x32_bf16 v[94:97], v[114:117], v[204:207], v[94:97]
	v_mfma_f32_16x16x32_bf16 v[90:93], v[122:125], v[204:207], v[90:93]
	v_mfma_f32_16x16x32_bf16 v[78:81], v[114:117], v[212:215], v[78:81]
	v_mfma_f32_16x16x32_bf16 v[74:77], v[122:125], v[212:215], v[74:77]
	v_mfma_f32_16x16x32_bf16 v[150:153], v[118:121], v[178:181], v[150:153]
	v_mfma_f32_16x16x32_bf16 v[146:149], v[126:129], v[178:181], v[146:149]
	v_mfma_f32_16x16x32_bf16 v[110:113], v[118:121], v[200:203], v[110:113]
	v_mfma_f32_16x16x32_bf16 v[106:109], v[126:129], v[200:203], v[106:109]
	v_mfma_f32_16x16x32_bf16 v[94:97], v[118:121], v[208:211], v[94:97]
	v_mfma_f32_16x16x32_bf16 v[90:93], v[126:129], v[208:211], v[90:93]
	v_mfma_f32_16x16x32_bf16 v[78:81], v[118:121], v[216:219], v[78:81]
	v_mfma_f32_16x16x32_bf16 v[74:77], v[126:129], v[216:219], v[74:77]
	s_setprio 0
	s_setprio 1
	v_mfma_f32_16x16x32_bf16 v[142:145], v[130:133], v[174:177], v[142:145]
	v_mfma_f32_16x16x32_bf16 v[138:141], v[166:169], v[174:177], v[138:141]
	v_mfma_f32_16x16x32_bf16 v[102:105], v[130:133], v[196:199], v[102:105]
	v_mfma_f32_16x16x32_bf16 v[98:101], v[166:169], v[196:199], v[98:101]
	v_mfma_f32_16x16x32_bf16 v[86:89], v[130:133], v[204:207], v[86:89]
	v_mfma_f32_16x16x32_bf16 v[82:85], v[166:169], v[204:207], v[82:85]
	v_mfma_f32_16x16x32_bf16 v[70:73], v[130:133], v[212:215], v[70:73]
	v_mfma_f32_16x16x32_bf16 v[66:69], v[166:169], v[212:215], v[66:69]
	s_setprio 2
	s_barrier
	v_mfma_f32_16x16x32_bf16 v[142:145], v[134:137], v[178:181], v[142:145]
	v_mfma_f32_16x16x32_bf16 v[138:141], v[170:173], v[178:181], v[138:141]
	v_mfma_f32_16x16x32_bf16 v[102:105], v[134:137], v[200:203], v[102:105]
	v_mfma_f32_16x16x32_bf16 v[98:101], v[170:173], v[200:203], v[98:101]
	v_mfma_f32_16x16x32_bf16 v[86:89], v[134:137], v[208:211], v[86:89]
	v_mfma_f32_16x16x32_bf16 v[82:85], v[170:173], v[208:211], v[82:85]
	v_mfma_f32_16x16x32_bf16 v[70:73], v[134:137], v[216:219], v[70:73]
	v_mfma_f32_16x16x32_bf16 v[66:69], v[170:173], v[216:219], v[66:69]
	s_setprio 0
	s_add_i32 s20, s52, s77
	s_add_u32 s100, s40, 0x80
	s_addc_u32 s101, s41, 0
	s_mov_b32 m0, s20
	ds_read_b128 v[174:177], v194 offset:16384
	ds_read_b128 v[178:181], v194 offset:17408
	ds_read_b128 v[196:199], v194 offset:18432
	ds_read_b128 v[200:203], v194 offset:19456
	ds_read_b128 v[204:207], v194 offset:20480
	ds_read_b128 v[208:211], v194 offset:21504
	ds_read_b128 v[212:215], v194 offset:22528
	ds_read_b128 v[216:219], v194 offset:23552
	global_load_lds_dwordx4 v0, s[40:41]
	s_add_i32 m0, s20, 0x2000
	s_add_i32 s3, s3, s77
	global_load_lds_dwordx4 v158, s[40:41]
	s_add_u32 s40, s40, s24
	s_addc_u32 s41, s41, s25
	s_mov_b32 m0, s3
	s_nop 0
	global_load_lds_dwordx4 v0, s[40:41]
	s_add_i32 m0, s3, 0x2000
	s_nop 0
	global_load_lds_dwordx4 v158, s[40:41]
	s_mov_b32 m0, s85
	s_nop 0
	global_load_lds_dwordx4 v154, s[44:45]
	s_mov_b32 m0, s92
	s_nop 0
	global_load_lds_dwordx4 v156, s[44:45]
	s_waitcnt vmcnt(8)
	s_waitcnt lgkmcnt(0)
	s_barrier
	s_setprio 1
	s_waitcnt lgkmcnt(0)
	v_mfma_f32_16x16x32_bf16 v[62:65], v[114:117], v[174:177], v[62:65]
	v_mfma_f32_16x16x32_bf16 v[58:61], v[122:125], v[174:177], v[58:61]
	v_mfma_f32_16x16x32_bf16 v[46:49], v[114:117], v[196:199], v[46:49]
	v_mfma_f32_16x16x32_bf16 v[42:45], v[122:125], v[196:199], v[42:45]
	v_mfma_f32_16x16x32_bf16 v[30:33], v[114:117], v[204:207], v[30:33]
	v_mfma_f32_16x16x32_bf16 v[26:29], v[122:125], v[204:207], v[26:29]
	v_mfma_f32_16x16x32_bf16 v[14:17], v[114:117], v[212:215], v[14:17]
	v_mfma_f32_16x16x32_bf16 v[10:13], v[122:125], v[212:215], v[10:13]
	v_mfma_f32_16x16x32_bf16 v[62:65], v[118:121], v[178:181], v[62:65]
	v_mfma_f32_16x16x32_bf16 v[58:61], v[126:129], v[178:181], v[58:61]
	v_mfma_f32_16x16x32_bf16 v[46:49], v[118:121], v[200:203], v[46:49]
	v_mfma_f32_16x16x32_bf16 v[42:45], v[126:129], v[200:203], v[42:45]
	v_mfma_f32_16x16x32_bf16 v[30:33], v[118:121], v[208:211], v[30:33]
	v_mfma_f32_16x16x32_bf16 v[26:29], v[126:129], v[208:211], v[26:29]
	v_mfma_f32_16x16x32_bf16 v[14:17], v[118:121], v[216:219], v[14:17]
	v_mfma_f32_16x16x32_bf16 v[10:13], v[126:129], v[216:219], v[10:13]
	s_setprio 0
	s_setprio 1
	v_mfma_f32_16x16x32_bf16 v[54:57], v[130:133], v[174:177], v[54:57]
	v_mfma_f32_16x16x32_bf16 v[50:53], v[166:169], v[174:177], v[50:53]
	v_mfma_f32_16x16x32_bf16 v[38:41], v[130:133], v[196:199], v[38:41]
	v_mfma_f32_16x16x32_bf16 v[34:37], v[166:169], v[196:199], v[34:37]
	v_mfma_f32_16x16x32_bf16 v[22:25], v[130:133], v[204:207], v[22:25]
	v_mfma_f32_16x16x32_bf16 v[18:21], v[166:169], v[204:207], v[18:21]
	v_mfma_f32_16x16x32_bf16 v[6:9], v[130:133], v[212:215], v[6:9]
	v_mfma_f32_16x16x32_bf16 v[2:5], v[166:169], v[212:215], v[2:5]
	s_setprio 2
	s_barrier
; #define PG8_STAGE(bufoff, gbase, voff) do { _Pragma("unroll") for (int _i = 0; _i < 2; ++_i) \
;         __builtin_amdgcn_global_load_lds((const unsigned*)((const char*)(gbase) + (voff)[_i]), (LAS unsigned*)(lds + (bufoff) + ldsw + _i * 8192), 16, 0, 0); } while (0)
; #define PG8_LDA(dst, b, h) do { _Pragma("unroll") for (int m = 0; m < 4; ++m) _Pragma("unroll") for (int k = 0; k < 2; ++k) dst[m][k] = *(const LAS bf16x8*)(lds + PG8_SA(b, h) + aoff + m * 2048 + k * 1024); } while (0)
; #define PG8_MMA(ai, bj, At, Bt) do { __builtin_amdgcn_s_setprio(1); _Pragma("unroll") for (int m = 0; m < 4; ++m) _Pragma("unroll") for (int n = 0; n < 2; ++n) _Pragma("unroll") for (int k = 0; k < 2; ++k) \
;         acc[ai][bj][m][n] = __builtin_amdgcn_mfma_f32_16x16x32_bf16(Bt[n][k], At[m][k], acc[ai][bj][m][n], 0, 0, 0); __builtin_amdgcn_s_setprio(0); } while (0)
; #define PG8_WAIT_V(n) asm volatile("s_waitcnt vmcnt(" #n ")" ::: "memory")
; #define PG8_WAIT_L(n) asm volatile("s_waitcnt lgkmcnt(" #n ")" ::: "memory")
; #define PG8_BAR __builtin_amdgcn_s_barrier()
; #define PG8_SCHED __builtin_amdgcn_sched_barrier(0)
; template <class Epi, class Sched>
; __device__ __forceinline__ void gemm_phase(LAS unsigned char* lds, const Gemm g, Sched S, const Epi& E) {
;     ...
;             PG8_WAIT_V(8); PG8_WAIT_L(0); PG8_BAR; PG8_MMA(0, 0, At, B0); PG8_MMA(0, 1, At, B1); PG8_BAR; PG8_SCHED;
;             PG8_LDA(At, 1, 1); PG8_STAGE(PG8_SB(1, 0), b3, voffB); PG8_STAGE(PG8_SB(1, 1), b3 + hstepB, voffB); PG8_STAGE(PG8_SA(1, 0), a3, voffA);
	v_mfma_f32_16x16x32_bf16 v[54:57], v[134:137], v[178:181], v[54:57]
	v_mfma_f32_16x16x32_bf16 v[50:53], v[170:173], v[178:181], v[50:53]
	v_mfma_f32_16x16x32_bf16 v[38:41], v[134:137], v[200:203], v[38:41]
	v_mfma_f32_16x16x32_bf16 v[34:37], v[170:173], v[200:203], v[34:37]
	v_mfma_f32_16x16x32_bf16 v[22:25], v[134:137], v[208:211], v[22:25]
	v_mfma_f32_16x16x32_bf16 v[18:21], v[170:173], v[208:211], v[18:21]
	v_mfma_f32_16x16x32_bf16 v[6:9], v[134:137], v[216:219], v[6:9]
	v_mfma_f32_16x16x32_bf16 v[2:5], v[170:173], v[216:219], v[2:5]
	s_setprio 0
	s_add_i32 s3, 0, 0x18000
	s_add_i32 s20, 0, 0x1c000
	v_add_u32_e32 v126, s3, v192
	v_add_u32_e32 v170, s20, v192
	ds_read_b128 v[114:117], v126
	ds_read_b128 v[118:121], v126 offset:1024
	ds_read_b128 v[122:125], v126 offset:2048
	ds_read_b128 v[126:129], v126 offset:3072
	ds_read_b128 v[130:133], v170
	ds_read_b128 v[134:137], v170 offset:1024
	ds_read_b128 v[166:169], v170 offset:2048
	ds_read_b128 v[170:173], v170 offset:3072
	s_add_u32 s40, s44, s8
	s_addc_u32 s41, s45, 0
	s_mov_b32 m0, s93
	ds_read_b128 v[174:177], v194 offset:32768
	ds_read_b128 v[178:181], v194 offset:33792
	ds_read_b128 v[196:199], v194 offset:34816
	ds_read_b128 v[200:203], v194 offset:35840
	ds_read_b128 v[204:207], v194 offset:36864
	ds_read_b128 v[208:211], v194 offset:37888
	ds_read_b128 v[212:215], v194 offset:38912
	ds_read_b128 v[216:219], v194 offset:39936
	global_load_lds_dwordx4 v154, s[40:41]
	s_mov_b32 m0, s94
	s_nop 0
	global_load_lds_dwordx4 v156, s[40:41]
	s_waitcnt vmcnt(8)
	s_waitcnt lgkmcnt(0)
	s_barrier
	s_setprio 1
	s_waitcnt lgkmcnt(0)
	v_mfma_f32_16x16x32_bf16 v[150:153], v[114:117], v[174:177], v[150:153]
	v_mfma_f32_16x16x32_bf16 v[146:149], v[122:125], v[174:177], v[146:149]
	v_mfma_f32_16x16x32_bf16 v[110:113], v[114:117], v[196:199], v[110:113]
	v_mfma_f32_16x16x32_bf16 v[106:109], v[122:125], v[196:199], v[106:109]
	v_mfma_f32_16x16x32_bf16 v[94:97], v[114:117], v[204:207], v[94:97]
	v_mfma_f32_16x16x32_bf16 v[90:93], v[122:125], v[204:207], v[90:93]
	v_mfma_f32_16x16x32_bf16 v[78:81], v[114:117], v[212:215], v[78:81]
	v_mfma_f32_16x16x32_bf16 v[74:77], v[122:125], v[212:215], v[74:77]
	v_mfma_f32_16x16x32_bf16 v[150:153], v[118:121], v[178:181], v[150:153]
	v_mfma_f32_16x16x32_bf16 v[146:149], v[126:129], v[178:181], v[146:149]
	v_mfma_f32_16x16x32_bf16 v[110:113], v[118:121], v[200:203], v[110:113]
	v_mfma_f32_16x16x32_bf16 v[106:109], v[126:129], v[200:203], v[106:109]
	v_mfma_f32_16x16x32_bf16 v[94:97], v[118:121], v[208:211], v[94:97]
	v_mfma_f32_16x16x32_bf16 v[90:93], v[126:129], v[208:211], v[90:93]
	v_mfma_f32_16x16x32_bf16 v[78:81], v[118:121], v[216:219], v[78:81]
	v_mfma_f32_16x16x32_bf16 v[74:77], v[126:129], v[216:219], v[74:77]
	s_setprio 0
	s_setprio 1
	v_mfma_f32_16x16x32_bf16 v[142:145], v[130:133], v[174:177], v[142:145]
	v_mfma_f32_16x16x32_bf16 v[138:141], v[166:169], v[174:177], v[138:141]
	v_mfma_f32_16x16x32_bf16 v[102:105], v[130:133], v[196:199], v[102:105]
	v_mfma_f32_16x16x32_bf16 v[98:101], v[166:169], v[196:199], v[98:101]
	v_mfma_f32_16x16x32_bf16 v[86:89], v[130:133], v[204:207], v[86:89]
	v_mfma_f32_16x16x32_bf16 v[82:85], v[166:169], v[204:207], v[82:85]
	v_mfma_f32_16x16x32_bf16 v[70:73], v[130:133], v[212:215], v[70:73]
	v_mfma_f32_16x16x32_bf16 v[66:69], v[166:169], v[212:215], v[66:69]
	s_setprio 2
	s_barrier
; #define PG8_STAGE(bufoff, gbase, voff) do { _Pragma("unroll") for (int _i = 0; _i < 2; ++_i) \
;         __builtin_amdgcn_global_load_lds((const unsigned*)((const char*)(gbase) + (voff)[_i]), (LAS unsigned*)(lds + (bufoff) + ldsw + _i * 8192), 16, 0, 0); } while (0)
; #define PG8_LDA(dst, b, h) do { _Pragma("unroll") for (int m = 0; m < 4; ++m) _Pragma("unroll") for (int k = 0; k < 2; ++k) dst[m][k] = *(const LAS bf16x8*)(lds + PG8_SA(b, h) + aoff + m * 2048 + k * 1024); } while (0)
; #define PG8_MMA(ai, bj, At, Bt) do { __builtin_amdgcn_s_setprio(1); _Pragma("unroll") for (int m = 0; m < 4; ++m) _Pragma("unroll") for (int n = 0; n < 2; ++n) _Pragma("unroll") for (int k = 0; k < 2; ++k) \
;         acc[ai][bj][m][n] = __builtin_amdgcn_mfma_f32_16x16x32_bf16(Bt[n][k], At[m][k], acc[ai][bj][m][n], 0, 0, 0); __builtin_amdgcn_s_setprio(0); } while (0)
; #define PG8_WAIT_V(n) asm volatile("s_waitcnt vmcnt(" #n ")" ::: "memory")
; #define PG8_WAIT_L(n) asm volatile("s_waitcnt lgkmcnt(" #n ")" ::: "memory")
; #define PG8_BAR __builtin_amdgcn_s_barrier()
; #define PG8_SCHED __builtin_amdgcn_sched_barrier(0)
; template <class Epi, class Sched>
; __device__ __forceinline__ void gemm_phase(LAS unsigned char* lds, const Gemm g, Sched S, const Epi& E) {
;     ...
;             PG8_LDA(At, 1, 1); PG8_STAGE(PG8_SB(1, 0), b3, voffB); PG8_STAGE(PG8_SB(1, 1), b3 + hstepB, voffB); PG8_STAGE(PG8_SA(1, 0), a3, voffA);
;             PG8_WAIT_V(8); PG8_WAIT_L(0); PG8_BAR; PG8_MMA(1, 0, At, B0); PG8_MMA(1, 1, At, B1); PG8_BAR; PG8_SCHED;
;     ...
;         if (wr == 0) PG8_BAR;
	v_mfma_f32_16x16x32_bf16 v[142:145], v[134:137], v[178:181], v[142:145]
	v_mfma_f32_16x16x32_bf16 v[138:141], v[170:173], v[178:181], v[138:141]
	v_mfma_f32_16x16x32_bf16 v[102:105], v[134:137], v[200:203], v[102:105]
	v_mfma_f32_16x16x32_bf16 v[98:101], v[170:173], v[200:203], v[98:101]
	v_mfma_f32_16x16x32_bf16 v[86:89], v[134:137], v[208:211], v[86:89]
	v_mfma_f32_16x16x32_bf16 v[82:85], v[170:173], v[208:211], v[82:85]
	v_mfma_f32_16x16x32_bf16 v[70:73], v[134:137], v[216:219], v[70:73]
	v_mfma_f32_16x16x32_bf16 v[66:69], v[170:173], v[216:219], v[66:69]
	s_setprio 0
	s_add_i32 s3, s3, s77
	s_mov_b32 m0, s3
	ds_read_b128 v[174:177], v194 offset:49152
	ds_read_b128 v[178:181], v194 offset:50176
	ds_read_b128 v[196:199], v194 offset:51200
	ds_read_b128 v[200:203], v194 offset:52224
	ds_read_b128 v[204:207], v194 offset:53248
	ds_read_b128 v[208:211], v194 offset:54272
	ds_read_b128 v[212:215], v194 offset:55296
	ds_read_b128 v[216:219], v194 offset:56320
	global_load_lds_dwordx4 v0, s[100:101]
	s_add_i32 m0, s3, 0x2000
	s_add_i32 s3, s20, s77
	global_load_lds_dwordx4 v158, s[100:101]
	s_add_u32 s100, s100, s24
	s_addc_u32 s101, s101, s25
	s_mov_b32 m0, s3
	s_nop 0
	global_load_lds_dwordx4 v0, s[100:101]
	s_add_i32 m0, s3, 0x2000
	s_nop 0
	global_load_lds_dwordx4 v158, s[100:101]
	s_add_u32 s100, s44, 0x80
	s_addc_u32 s101, s45, 0
	s_mov_b32 m0, s97
	s_nop 0
	global_load_lds_dwordx4 v154, s[100:101]
	s_mov_b32 m0, s98
	s_nop 0
	global_load_lds_dwordx4 v156, s[100:101]
	s_waitcnt vmcnt(8)
	s_waitcnt lgkmcnt(0)
	s_barrier
	s_setprio 1
	s_waitcnt lgkmcnt(0)
	v_mfma_f32_16x16x32_bf16 v[62:65], v[114:117], v[174:177], v[62:65]
	v_mfma_f32_16x16x32_bf16 v[58:61], v[122:125], v[174:177], v[58:61]
	v_mfma_f32_16x16x32_bf16 v[46:49], v[114:117], v[196:199], v[46:49]
	v_mfma_f32_16x16x32_bf16 v[42:45], v[122:125], v[196:199], v[42:45]
	v_mfma_f32_16x16x32_bf16 v[30:33], v[114:117], v[204:207], v[30:33]
	v_mfma_f32_16x16x32_bf16 v[26:29], v[122:125], v[204:207], v[26:29]
	v_mfma_f32_16x16x32_bf16 v[14:17], v[114:117], v[212:215], v[14:17]
	v_mfma_f32_16x16x32_bf16 v[10:13], v[122:125], v[212:215], v[10:13]
	v_mfma_f32_16x16x32_bf16 v[62:65], v[118:121], v[178:181], v[62:65]
	v_mfma_f32_16x16x32_bf16 v[58:61], v[126:129], v[178:181], v[58:61]
	v_mfma_f32_16x16x32_bf16 v[46:49], v[118:121], v[200:203], v[46:49]
	v_mfma_f32_16x16x32_bf16 v[42:45], v[126:129], v[200:203], v[42:45]
	v_mfma_f32_16x16x32_bf16 v[30:33], v[118:121], v[208:211], v[30:33]
	v_mfma_f32_16x16x32_bf16 v[26:29], v[126:129], v[208:211], v[26:29]
	v_mfma_f32_16x16x32_bf16 v[14:17], v[118:121], v[216:219], v[14:17]
	v_mfma_f32_16x16x32_bf16 v[10:13], v[126:129], v[216:219], v[10:13]
	s_setprio 0
	s_setprio 1
	v_mfma_f32_16x16x32_bf16 v[54:57], v[130:133], v[174:177], v[54:57]
	v_mfma_f32_16x16x32_bf16 v[50:53], v[166:169], v[174:177], v[50:53]
	v_mfma_f32_16x16x32_bf16 v[38:41], v[130:133], v[196:199], v[38:41]
	v_mfma_f32_16x16x32_bf16 v[34:37], v[166:169], v[196:199], v[34:37]
	v_mfma_f32_16x16x32_bf16 v[22:25], v[130:133], v[204:207], v[22:25]
	v_mfma_f32_16x16x32_bf16 v[18:21], v[166:169], v[204:207], v[18:21]
	v_mfma_f32_16x16x32_bf16 v[6:9], v[130:133], v[212:215], v[6:9]
	v_mfma_f32_16x16x32_bf16 v[2:5], v[166:169], v[212:215], v[2:5]
	s_setprio 2
	s_barrier
	v_mfma_f32_16x16x32_bf16 v[54:57], v[134:137], v[178:181], v[54:57]
	v_mfma_f32_16x16x32_bf16 v[50:53], v[170:173], v[178:181], v[50:53]
	v_mfma_f32_16x16x32_bf16 v[38:41], v[134:137], v[200:203], v[38:41]
	v_mfma_f32_16x16x32_bf16 v[34:37], v[170:173], v[200:203], v[34:37]
	v_mfma_f32_16x16x32_bf16 v[22:25], v[134:137], v[208:211], v[22:25]
	v_mfma_f32_16x16x32_bf16 v[18:21], v[170:173], v[208:211], v[18:21]
	v_mfma_f32_16x16x32_bf16 v[6:9], v[134:137], v[216:219], v[6:9]
	v_mfma_f32_16x16x32_bf16 v[2:5], v[170:173], v[216:219], v[2:5]
	s_setprio 0
	s_add_u32 s11, s11, 0x100
	s_addc_u32 s19, s19, 0
	s_add_u32 s42, s42, 0x100
	s_addc_u32 s43, s43, 0
	s_cmp_ge_u32 s21, s96
	s_mov_b32 s20, s21
	s_cbranch_scc0 .LBB0_727
	s_and_b64 vcc, exec, s[30:31]
	s_cbranch_vccz .LBB0_730
	s_barrier

; #define PG8_STAGE(bufoff, gbase, voff) do { _Pragma("unroll") for (int _i = 0; _i < 2; ++_i) \
;         __builtin_amdgcn_global_load_lds((const unsigned*)((const char*)(gbase) + (voff)[_i]), (LAS unsigned*)(lds + (bufoff) + ldsw + _i * 8192), 16, 0, 0); } while (0)
; #define PG8_LDA(dst, b, h) do { _Pragma("unroll") for (int m = 0; m < 4; ++m) _Pragma("unroll") for (int k = 0; k < 2; ++k) dst[m][k] = *(const LAS bf16x8*)(lds + PG8_SA(b, h) + aoff + m * 2048 + k * 1024); } while (0)
; #define PG8_LDB(dst, b, h) do { _Pragma("unroll") for (int n = 0; n < 2; ++n) _Pragma("unroll") for (int k = 0; k < 2; ++k) dst[n][k] = *(const LAS bf16x8*)(lds + PG8_SB(b, h) + boff + n * 2048 + k * 1024); } while (0)
; #define PG8_WAIT_V(n) asm volatile("s_waitcnt vmcnt(" #n ")" ::: "memory")
; #define PG8_WAIT_L(n) asm volatile("s_waitcnt lgkmcnt(" #n ")" ::: "memory")
; #define PG8_BAR __builtin_amdgcn_s_barrier()
; template <class Epi, class Sched>
; __device__ __forceinline__ void gemm_phase(LAS unsigned char* lds, const Gemm g, Sched S, const Epi& E) {
;     ...
;         const bool has_next = S.next(ui + 1, nxt);
;         const char* nA = has_next ? (const char*)g.A + a_off(g, nxt) : cA; const char* nB = has_next ? (const char*)g.Bt + b_off(g, nxt) : cB;
;         for (int t = 0; t < nt; t += 2) {
;             const bool last = (t == nt - 2);
;             const char* a1 = cA + (size_t)(t + 1) * kstep;
;             const char* a2 = last ? nA : cA + (size_t)(t + 2) * kstep; const char* b2 = last ? nB : cB + (size_t)(t + 2) * kstep;
;             const char* a3 = a2 + kstep; const char* b3 = b2 + kstep;
;             PG8_LDB(B0, 0, 0); PG8_LDB(B1, 0, 1); PG8_SCHED; PG8_LDA(At, 0, 0); PG8_STAGE(PG8_SA(1, 1), a1 + hstepA, voffA);
;             PG8_WAIT_V(8); PG8_WAIT_L(0); PG8_BAR; PG8_MMA(0, 0, At, B0); PG8_MMA(0, 1, At, B1); PG8_BAR; PG8_SCHED;
;             PG8_LDA(At, 0, 1); PG8_STAGE(PG8_SB(0, 0), b2, voffB); PG8_STAGE(PG8_SB(0, 1), b2 + hstepB, voffB); PG8_STAGE(PG8_SA(0, 0), a2, voffA);
;             PG8_WAIT_V(8); PG8_WAIT_L(0); PG8_BAR; PG8_MMA(1, 0, At, B0); PG8_MMA(1, 1, At, B1); PG8_BAR; PG8_SCHED;
;             PG8_LDB(B0, 1, 0); PG8_LDB(B1, 1, 1); PG8_SCHED; PG8_LDA(At, 1, 0); PG8_STAGE(PG8_SA(0, 1), a2 + hstepA, voffA);
;             PG8_WAIT_V(8); PG8_WAIT_L(0); PG8_BAR; PG8_MMA(0, 0, At, B0); PG8_MMA(0, 1, At, B1); PG8_BAR; PG8_SCHED;
.LBB0_770:
	s_add_u32 s3, s10, 0xfffc0080
	s_addc_u32 s42, s11, -1
	s_add_i32 s71, 0, 0x10000
	s_cmp_eq_u32 s70, 12
	s_cselect_b32 s45, s60, s42
	s_cselect_b32 s44, s61, s3
	s_cselect_b32 s43, s62, s65
	s_cselect_b32 s42, s63, s64
	s_add_i32 s3, 0, 0x14000
	v_add_u32_e32 v142, s71, v183
	v_add_u32_e32 v158, s3, v183
	ds_read_b128 v[130:133], v142
	ds_read_b128 v[134:137], v142 offset:1024
	ds_read_b128 v[138:141], v142 offset:2048
	ds_read_b128 v[142:145], v142 offset:3072
	ds_read_b128 v[146:149], v158
	ds_read_b128 v[150:153], v158 offset:1024
	ds_read_b128 v[154:157], v158 offset:2048
	ds_read_b128 v[158:161], v158 offset:3072
	s_add_i32 m0, s9, 0xc000
	ds_read_b128 v[174:177], v194
	ds_read_b128 v[196:199], v194 offset:1024
	ds_read_b128 v[200:203], v194 offset:2048
	ds_read_b128 v[204:207], v194 offset:3072
	ds_read_b128 v[208:211], v194 offset:4096
	ds_read_b128 v[212:215], v194 offset:5120
	ds_read_b128 v[216:219], v194 offset:6144
	ds_read_b128 v[220:223], v194 offset:7168
	global_load_lds_dwordx4 v172, s[10:11]
	s_add_i32 m0, s9, 0xe000
	s_nop 0
	global_load_lds_dwordx4 v170, s[10:11]
	s_waitcnt vmcnt(8)
	s_waitcnt lgkmcnt(0)
	s_barrier
	s_setprio 1
	s_waitcnt lgkmcnt(0)
	v_mfma_f32_16x16x32_bf16 v[126:129], v[130:133], v[174:177], v[126:129]
	v_mfma_f32_16x16x32_bf16 v[118:121], v[138:141], v[174:177], v[118:121]
	v_mfma_f32_16x16x32_bf16 v[110:113], v[130:133], v[200:203], v[110:113]
	v_mfma_f32_16x16x32_bf16 v[102:105], v[138:141], v[200:203], v[102:105]
	v_mfma_f32_16x16x32_bf16 v[94:97], v[130:133], v[208:211], v[94:97]
	v_mfma_f32_16x16x32_bf16 v[86:89], v[138:141], v[208:211], v[86:89]
	v_mfma_f32_16x16x32_bf16 v[78:81], v[130:133], v[216:219], v[78:81]
	v_mfma_f32_16x16x32_bf16 v[70:73], v[138:141], v[216:219], v[70:73]
	v_mfma_f32_16x16x32_bf16 v[126:129], v[134:137], v[196:199], v[126:129]
	v_mfma_f32_16x16x32_bf16 v[118:121], v[142:145], v[196:199], v[118:121]
	v_mfma_f32_16x16x32_bf16 v[110:113], v[134:137], v[204:207], v[110:113]
	v_mfma_f32_16x16x32_bf16 v[102:105], v[142:145], v[204:207], v[102:105]
	v_mfma_f32_16x16x32_bf16 v[94:97], v[134:137], v[212:215], v[94:97]
	v_mfma_f32_16x16x32_bf16 v[86:89], v[142:145], v[212:215], v[86:89]
	v_mfma_f32_16x16x32_bf16 v[78:81], v[134:137], v[220:223], v[78:81]
	v_mfma_f32_16x16x32_bf16 v[70:73], v[142:145], v[220:223], v[70:73]
	s_setprio 0
	s_setprio 1
	v_mfma_f32_16x16x32_bf16 v[122:125], v[146:149], v[174:177], v[122:125]
	v_mfma_f32_16x16x32_bf16 v[114:117], v[154:157], v[174:177], v[114:117]
	v_mfma_f32_16x16x32_bf16 v[106:109], v[146:149], v[200:203], v[106:109]
	v_mfma_f32_16x16x32_bf16 v[98:101], v[154:157], v[200:203], v[98:101]
	v_mfma_f32_16x16x32_bf16 v[90:93], v[146:149], v[208:211], v[90:93]
	v_mfma_f32_16x16x32_bf16 v[82:85], v[154:157], v[208:211], v[82:85]
	v_mfma_f32_16x16x32_bf16 v[74:77], v[146:149], v[216:219], v[74:77]
	v_mfma_f32_16x16x32_bf16 v[66:69], v[154:157], v[216:219], v[66:69]
	s_setprio 2
	s_barrier
	v_mfma_f32_16x16x32_bf16 v[122:125], v[150:153], v[196:199], v[122:125]
	v_mfma_f32_16x16x32_bf16 v[114:117], v[158:161], v[196:199], v[114:117]
	v_mfma_f32_16x16x32_bf16 v[106:109], v[150:153], v[204:207], v[106:109]
	v_mfma_f32_16x16x32_bf16 v[98:101], v[158:161], v[204:207], v[98:101]
	v_mfma_f32_16x16x32_bf16 v[90:93], v[150:153], v[212:215], v[90:93]
	v_mfma_f32_16x16x32_bf16 v[82:85], v[158:161], v[212:215], v[82:85]
	v_mfma_f32_16x16x32_bf16 v[74:77], v[150:153], v[220:223], v[74:77]
	v_mfma_f32_16x16x32_bf16 v[66:69], v[158:161], v[220:223], v[66:69]
	s_setprio 0
	s_add_i32 s71, s71, s7
	s_mov_b32 m0, s71
	ds_read_b128 v[174:177], v194 offset:16384
	ds_read_b128 v[196:199], v194 offset:17408
	ds_read_b128 v[200:203], v194 offset:18432
	ds_read_b128 v[204:207], v194 offset:19456
	ds_read_b128 v[208:211], v194 offset:20480
	ds_read_b128 v[212:215], v194 offset:21504
	ds_read_b128 v[216:219], v194 offset:22528
	ds_read_b128 v[220:223], v194 offset:23552
	global_load_lds_dwordx4 v0, s[42:43]
	s_add_i32 m0, s71, 0x2000
	s_add_u32 s96, s42, 0x40000
	s_addc_u32 s97, s43, 0
	s_add_i32 s3, s3, s7
	global_load_lds_dwordx4 v164, s[42:43]
	s_mov_b32 m0, s3
	s_nop 0
	global_load_lds_dwordx4 v0, s[96:97]
	s_add_i32 m0, s3, 0x2000
	s_nop 0
	global_load_lds_dwordx4 v164, s[96:97]
	s_mov_b32 m0, s9
	s_nop 0
	global_load_lds_dwordx4 v168, s[44:45]
	s_mov_b32 m0, s56
	s_nop 0
	global_load_lds_dwordx4 v166, s[44:45]
	s_waitcnt vmcnt(8)
	s_waitcnt lgkmcnt(0)
	s_barrier
	s_setprio 1
	s_waitcnt lgkmcnt(0)
	v_mfma_f32_16x16x32_bf16 v[62:65], v[130:133], v[174:177], v[62:65]
	v_mfma_f32_16x16x32_bf16 v[54:57], v[138:141], v[174:177], v[54:57]
	v_mfma_f32_16x16x32_bf16 v[46:49], v[130:133], v[200:203], v[46:49]
	v_mfma_f32_16x16x32_bf16 v[38:41], v[138:141], v[200:203], v[38:41]
	v_mfma_f32_16x16x32_bf16 v[30:33], v[130:133], v[208:211], v[30:33]
	v_mfma_f32_16x16x32_bf16 v[22:25], v[138:141], v[208:211], v[22:25]
	v_mfma_f32_16x16x32_bf16 v[14:17], v[130:133], v[216:219], v[14:17]
	v_mfma_f32_16x16x32_bf16 v[6:9], v[138:141], v[216:219], v[6:9]
	v_mfma_f32_16x16x32_bf16 v[62:65], v[134:137], v[196:199], v[62:65]
	v_mfma_f32_16x16x32_bf16 v[54:57], v[142:145], v[196:199], v[54:57]
	v_mfma_f32_16x16x32_bf16 v[46:49], v[134:137], v[204:207], v[46:49]
	v_mfma_f32_16x16x32_bf16 v[38:41], v[142:145], v[204:207], v[38:41]
	v_mfma_f32_16x16x32_bf16 v[30:33], v[134:137], v[212:215], v[30:33]
	v_mfma_f32_16x16x32_bf16 v[22:25], v[142:145], v[212:215], v[22:25]
	v_mfma_f32_16x16x32_bf16 v[14:17], v[134:137], v[220:223], v[14:17]
	v_mfma_f32_16x16x32_bf16 v[6:9], v[142:145], v[220:223], v[6:9]
	s_setprio 0
	s_setprio 1
	v_mfma_f32_16x16x32_bf16 v[58:61], v[146:149], v[174:177], v[58:61]
	v_mfma_f32_16x16x32_bf16 v[50:53], v[154:157], v[174:177], v[50:53]
	v_mfma_f32_16x16x32_bf16 v[42:45], v[146:149], v[200:203], v[42:45]
	v_mfma_f32_16x16x32_bf16 v[34:37], v[154:157], v[200:203], v[34:37]
	v_mfma_f32_16x16x32_bf16 v[26:29], v[146:149], v[208:211], v[26:29]
	v_mfma_f32_16x16x32_bf16 v[18:21], v[154:157], v[208:211], v[18:21]
	v_mfma_f32_16x16x32_bf16 v[10:13], v[146:149], v[216:219], v[10:13]
	v_mfma_f32_16x16x32_bf16 v[2:5], v[154:157], v[216:219], v[2:5]
	s_setprio 2
	s_barrier
; #define PG8_STAGE(bufoff, gbase, voff) do { _Pragma("unroll") for (int _i = 0; _i < 2; ++_i) \
;         __builtin_amdgcn_global_load_lds((const unsigned*)((const char*)(gbase) + (voff)[_i]), (LAS unsigned*)(lds + (bufoff) + ldsw + _i * 8192), 16, 0, 0); } while (0)
; #define PG8_LDA(dst, b, h) do { _Pragma("unroll") for (int m = 0; m < 4; ++m) _Pragma("unroll") for (int k = 0; k < 2; ++k) dst[m][k] = *(const LAS bf16x8*)(lds + PG8_SA(b, h) + aoff + m * 2048 + k * 1024); } while (0)
; #define PG8_MMA(ai, bj, At, Bt) do { __builtin_amdgcn_s_setprio(1); _Pragma("unroll") for (int m = 0; m < 4; ++m) _Pragma("unroll") for (int n = 0; n < 2; ++n) _Pragma("unroll") for (int k = 0; k < 2; ++k) \
;         acc[ai][bj][m][n] = __builtin_amdgcn_mfma_f32_16x16x32_bf16(Bt[n][k], At[m][k], acc[ai][bj][m][n], 0, 0, 0); __builtin_amdgcn_s_setprio(0); } while (0)
; #define PG8_WAIT_V(n) asm volatile("s_waitcnt vmcnt(" #n ")" ::: "memory")
; #define PG8_WAIT_L(n) asm volatile("s_waitcnt lgkmcnt(" #n ")" ::: "memory")
; #define PG8_BAR __builtin_amdgcn_s_barrier()
; #define PG8_SCHED __builtin_amdgcn_sched_barrier(0)
; template <class Epi, class Sched>
; __device__ __forceinline__ void gemm_phase(LAS unsigned char* lds, const Gemm g, Sched S, const Epi& E) {
;     ...
;             PG8_WAIT_V(8); PG8_WAIT_L(0); PG8_BAR; PG8_MMA(0, 0, At, B0); PG8_MMA(0, 1, At, B1); PG8_BAR; PG8_SCHED;
;             PG8_LDA(At, 1, 1); PG8_STAGE(PG8_SB(1, 0), b3, voffB); PG8_STAGE(PG8_SB(1, 1), b3 + hstepB, voffB); PG8_STAGE(PG8_SA(1, 0), a3, voffA);
	v_mfma_f32_16x16x32_bf16 v[58:61], v[150:153], v[196:199], v[58:61]
	v_mfma_f32_16x16x32_bf16 v[50:53], v[158:161], v[196:199], v[50:53]
	v_mfma_f32_16x16x32_bf16 v[42:45], v[150:153], v[204:207], v[42:45]
	v_mfma_f32_16x16x32_bf16 v[34:37], v[158:161], v[204:207], v[34:37]
	v_mfma_f32_16x16x32_bf16 v[26:29], v[150:153], v[212:215], v[26:29]
	v_mfma_f32_16x16x32_bf16 v[18:21], v[158:161], v[212:215], v[18:21]
	v_mfma_f32_16x16x32_bf16 v[10:13], v[150:153], v[220:223], v[10:13]
	v_mfma_f32_16x16x32_bf16 v[2:5], v[158:161], v[220:223], v[2:5]
	s_setprio 0
	s_add_i32 s3, 0, 0x18000
	s_add_i32 s71, 0, 0x1c000
	v_add_u32_e32 v142, s3, v183
	v_add_u32_e32 v158, s71, v183
	ds_read_b128 v[130:133], v142
	ds_read_b128 v[134:137], v142 offset:1024
	ds_read_b128 v[138:141], v142 offset:2048
	ds_read_b128 v[142:145], v142 offset:3072
	ds_read_b128 v[146:149], v158
	ds_read_b128 v[150:153], v158 offset:1024
	ds_read_b128 v[154:157], v158 offset:2048
	ds_read_b128 v[158:161], v158 offset:3072
	s_add_u32 s44, s44, 0x40000
	s_addc_u32 s45, s45, 0
	s_mov_b32 m0, s67
	ds_read_b128 v[174:177], v194 offset:32768
	ds_read_b128 v[196:199], v194 offset:33792
	ds_read_b128 v[200:203], v194 offset:34816
	ds_read_b128 v[204:207], v194 offset:35840
	ds_read_b128 v[208:211], v194 offset:36864
	ds_read_b128 v[212:215], v194 offset:37888
	ds_read_b128 v[216:219], v194 offset:38912
	ds_read_b128 v[220:223], v194 offset:39936
	global_load_lds_dwordx4 v168, s[44:45]
	s_mov_b32 m0, s72
	s_nop 0
	global_load_lds_dwordx4 v166, s[44:45]
	s_waitcnt vmcnt(8)
	s_waitcnt lgkmcnt(0)
	s_barrier
	s_setprio 1
	s_waitcnt lgkmcnt(0)
	v_mfma_f32_16x16x32_bf16 v[126:129], v[130:133], v[174:177], v[126:129]
	v_mfma_f32_16x16x32_bf16 v[118:121], v[138:141], v[174:177], v[118:121]
	v_mfma_f32_16x16x32_bf16 v[110:113], v[130:133], v[200:203], v[110:113]
	v_mfma_f32_16x16x32_bf16 v[102:105], v[138:141], v[200:203], v[102:105]
	v_mfma_f32_16x16x32_bf16 v[94:97], v[130:133], v[208:211], v[94:97]
	v_mfma_f32_16x16x32_bf16 v[86:89], v[138:141], v[208:211], v[86:89]
	v_mfma_f32_16x16x32_bf16 v[78:81], v[130:133], v[216:219], v[78:81]
	v_mfma_f32_16x16x32_bf16 v[70:73], v[138:141], v[216:219], v[70:73]
	v_mfma_f32_16x16x32_bf16 v[126:129], v[134:137], v[196:199], v[126:129]
	v_mfma_f32_16x16x32_bf16 v[118:121], v[142:145], v[196:199], v[118:121]
	v_mfma_f32_16x16x32_bf16 v[110:113], v[134:137], v[204:207], v[110:113]
	v_mfma_f32_16x16x32_bf16 v[102:105], v[142:145], v[204:207], v[102:105]
	v_mfma_f32_16x16x32_bf16 v[94:97], v[134:137], v[212:215], v[94:97]
	v_mfma_f32_16x16x32_bf16 v[86:89], v[142:145], v[212:215], v[86:89]
	v_mfma_f32_16x16x32_bf16 v[78:81], v[134:137], v[220:223], v[78:81]
	v_mfma_f32_16x16x32_bf16 v[70:73], v[142:145], v[220:223], v[70:73]
	s_setprio 0
	s_setprio 1
	v_mfma_f32_16x16x32_bf16 v[122:125], v[146:149], v[174:177], v[122:125]
	v_mfma_f32_16x16x32_bf16 v[114:117], v[154:157], v[174:177], v[114:117]
	v_mfma_f32_16x16x32_bf16 v[106:109], v[146:149], v[200:203], v[106:109]
	v_mfma_f32_16x16x32_bf16 v[98:101], v[154:157], v[200:203], v[98:101]
	v_mfma_f32_16x16x32_bf16 v[90:93], v[146:149], v[208:211], v[90:93]
	v_mfma_f32_16x16x32_bf16 v[82:85], v[154:157], v[208:211], v[82:85]
	v_mfma_f32_16x16x32_bf16 v[74:77], v[146:149], v[216:219], v[74:77]
	v_mfma_f32_16x16x32_bf16 v[66:69], v[154:157], v[216:219], v[66:69]
	s_setprio 2
	s_barrier
; #define PG8_STAGE(bufoff, gbase, voff) do { _Pragma("unroll") for (int _i = 0; _i < 2; ++_i) \
;         __builtin_amdgcn_global_load_lds((const unsigned*)((const char*)(gbase) + (voff)[_i]), (LAS unsigned*)(lds + (bufoff) + ldsw + _i * 8192), 16, 0, 0); } while (0)
; #define PG8_LDA(dst, b, h) do { _Pragma("unroll") for (int m = 0; m < 4; ++m) _Pragma("unroll") for (int k = 0; k < 2; ++k) dst[m][k] = *(const LAS bf16x8*)(lds + PG8_SA(b, h) + aoff + m * 2048 + k * 1024); } while (0)
; #define PG8_MMA(ai, bj, At, Bt) do { __builtin_amdgcn_s_setprio(1); _Pragma("unroll") for (int m = 0; m < 4; ++m) _Pragma("unroll") for (int n = 0; n < 2; ++n) _Pragma("unroll") for (int k = 0; k < 2; ++k) \
;         acc[ai][bj][m][n] = __builtin_amdgcn_mfma_f32_16x16x32_bf16(Bt[n][k], At[m][k], acc[ai][bj][m][n], 0, 0, 0); __builtin_amdgcn_s_setprio(0); } while (0)
; #define PG8_WAIT_V(n) asm volatile("s_waitcnt vmcnt(" #n ")" ::: "memory")
; #define PG8_WAIT_L(n) asm volatile("s_waitcnt lgkmcnt(" #n ")" ::: "memory")
; #define PG8_BAR __builtin_amdgcn_s_barrier()
; #define PG8_SCHED __builtin_amdgcn_sched_barrier(0)
; template <class Epi, class Sched>
; __device__ __forceinline__ void gemm_phase(LAS unsigned char* lds, const Gemm g, Sched S, const Epi& E) {
;     ...
;             PG8_LDA(At, 1, 1); PG8_STAGE(PG8_SB(1, 0), b3, voffB); PG8_STAGE(PG8_SB(1, 1), b3 + hstepB, voffB); PG8_STAGE(PG8_SA(1, 0), a3, voffA);
;             PG8_WAIT_V(8); PG8_WAIT_L(0); PG8_BAR; PG8_MMA(1, 0, At, B0); PG8_MMA(1, 1, At, B1); PG8_BAR; PG8_SCHED;
	v_mfma_f32_16x16x32_bf16 v[122:125], v[150:153], v[196:199], v[122:125]
	v_mfma_f32_16x16x32_bf16 v[114:117], v[158:161], v[196:199], v[114:117]
	v_mfma_f32_16x16x32_bf16 v[106:109], v[150:153], v[204:207], v[106:109]
	v_mfma_f32_16x16x32_bf16 v[98:101], v[158:161], v[204:207], v[98:101]
	v_mfma_f32_16x16x32_bf16 v[90:93], v[150:153], v[212:215], v[90:93]
	v_mfma_f32_16x16x32_bf16 v[82:85], v[158:161], v[212:215], v[82:85]
	v_mfma_f32_16x16x32_bf16 v[74:77], v[150:153], v[220:223], v[74:77]
	v_mfma_f32_16x16x32_bf16 v[66:69], v[158:161], v[220:223], v[66:69]
	s_setprio 0
	s_add_i32 s3, s3, s7
	s_add_u32 s100, s42, 0x80
	s_addc_u32 s101, s43, 0
	s_mov_b32 m0, s3
	ds_read_b128 v[174:177], v194 offset:49152
	ds_read_b128 v[196:199], v194 offset:50176
	ds_read_b128 v[200:203], v194 offset:51200
	ds_read_b128 v[204:207], v194 offset:52224
	ds_read_b128 v[208:211], v194 offset:53248
	ds_read_b128 v[212:215], v194 offset:54272
	ds_read_b128 v[216:219], v194 offset:55296
	ds_read_b128 v[220:223], v194 offset:56320
	global_load_lds_dwordx4 v0, s[100:101]
	s_add_i32 m0, s3, 0x2000
	s_add_u32 s42, s42, 0x40080
	s_addc_u32 s43, s43, 0
	s_add_u32 s96, s44, 0xfffc0080
	s_addc_u32 s97, s45, -1
	s_add_i32 s3, s71, s7
	global_load_lds_dwordx4 v164, s[100:101]
	s_mov_b32 m0, s3
	s_nop 0
	global_load_lds_dwordx4 v0, s[42:43]
	s_add_i32 m0, s3, 0x2000
	s_nop 0
	global_load_lds_dwordx4 v164, s[42:43]
	s_mov_b32 m0, s73
	s_nop 0
	global_load_lds_dwordx4 v168, s[96:97]
	s_mov_b32 m0, s76
	s_nop 0
	global_load_lds_dwordx4 v166, s[96:97]
	s_waitcnt vmcnt(8)
	s_waitcnt lgkmcnt(0)
	s_barrier
	s_setprio 1
	s_waitcnt lgkmcnt(0)
	v_mfma_f32_16x16x32_bf16 v[62:65], v[130:133], v[174:177], v[62:65]
	v_mfma_f32_16x16x32_bf16 v[54:57], v[138:141], v[174:177], v[54:57]
	v_mfma_f32_16x16x32_bf16 v[46:49], v[130:133], v[200:203], v[46:49]
	v_mfma_f32_16x16x32_bf16 v[38:41], v[138:141], v[200:203], v[38:41]
	v_mfma_f32_16x16x32_bf16 v[30:33], v[130:133], v[208:211], v[30:33]
	v_mfma_f32_16x16x32_bf16 v[22:25], v[138:141], v[208:211], v[22:25]
	v_mfma_f32_16x16x32_bf16 v[14:17], v[130:133], v[216:219], v[14:17]
	v_mfma_f32_16x16x32_bf16 v[6:9], v[138:141], v[216:219], v[6:9]
	v_mfma_f32_16x16x32_bf16 v[62:65], v[134:137], v[196:199], v[62:65]
	v_mfma_f32_16x16x32_bf16 v[54:57], v[142:145], v[196:199], v[54:57]
	v_mfma_f32_16x16x32_bf16 v[46:49], v[134:137], v[204:207], v[46:49]
	v_mfma_f32_16x16x32_bf16 v[38:41], v[142:145], v[204:207], v[38:41]
	v_mfma_f32_16x16x32_bf16 v[30:33], v[134:137], v[212:215], v[30:33]
	v_mfma_f32_16x16x32_bf16 v[22:25], v[142:145], v[212:215], v[22:25]
	v_mfma_f32_16x16x32_bf16 v[14:17], v[134:137], v[220:223], v[14:17]
	v_mfma_f32_16x16x32_bf16 v[6:9], v[142:145], v[220:223], v[6:9]
	s_setprio 0
	s_setprio 1
	v_mfma_f32_16x16x32_bf16 v[58:61], v[146:149], v[174:177], v[58:61]
	v_mfma_f32_16x16x32_bf16 v[50:53], v[154:157], v[174:177], v[50:53]
	v_mfma_f32_16x16x32_bf16 v[42:45], v[146:149], v[200:203], v[42:45]
	v_mfma_f32_16x16x32_bf16 v[34:37], v[154:157], v[200:203], v[34:37]
	v_mfma_f32_16x16x32_bf16 v[26:29], v[146:149], v[208:211], v[26:29]
	v_mfma_f32_16x16x32_bf16 v[18:21], v[154:157], v[208:211], v[18:21]
	v_mfma_f32_16x16x32_bf16 v[10:13], v[146:149], v[216:219], v[10:13]
	v_mfma_f32_16x16x32_bf16 v[2:5], v[154:157], v[216:219], v[2:5]
	s_setprio 2
	s_barrier
	v_mfma_f32_16x16x32_bf16 v[58:61], v[150:153], v[196:199], v[58:61]
	v_mfma_f32_16x16x32_bf16 v[50:53], v[158:161], v[196:199], v[50:53]
	v_mfma_f32_16x16x32_bf16 v[42:45], v[150:153], v[204:207], v[42:45]
	v_mfma_f32_16x16x32_bf16 v[34:37], v[158:161], v[204:207], v[34:37]
	v_mfma_f32_16x16x32_bf16 v[26:29], v[150:153], v[212:215], v[26:29]
	v_mfma_f32_16x16x32_bf16 v[18:21], v[158:161], v[212:215], v[18:21]
	v_mfma_f32_16x16x32_bf16 v[10:13], v[150:153], v[220:223], v[10:13]
	v_mfma_f32_16x16x32_bf16 v[2:5], v[158:161], v[220:223], v[2:5]
	s_setprio 0
	s_add_i32 s70, s70, 2
	s_add_u32 s64, s64, 0x100
	s_addc_u32 s65, s65, 0
	s_add_u32 s10, s10, 0x100
	s_addc_u32 s11, s11, 0
	s_cmp_gt_u32 s70, 13
	s_cbranch_scc0 .LBB0_770
	s_and_b64 vcc, exec, s[30:31]
	s_cbranch_vccz .LBB0_773
	s_barrier
